# v32 + GEMM accumulator zeroing at tile boundaries with v_mov_b64 (63 instead of 126 moves) + prologue PLE-proj item assigned to waves with one fewer gate/up item
# speedup vs baseline: 1.0154x; 1.0154x over previous
; template <class Epi, class Sched, bool ALIGN_EPI = false, bool SP2 = false>
; __device__ __forceinline__ void gemm_phase(const int g_wave, PG8_LAS unsigned char* lds, const Gemm g, const Sched& S, const Epi& E) {
;     ...
;     for (;;) {
;         const bool has_next = S.next(ui + 1, nxt);
;         const char* nA = has_next ? (const char*)g.A + (size_t)nxt.pm * tstep : cA; const char* nB = has_next ? (const char*)g.Bt + (size_t)nxt.pn * tstep : cB;
;     ...
; #pragma unroll
;         for (int a = 0; a < 2; ++a)
; #pragma unroll
;             for (int b = 0; b < 2; ++b)
; #pragma unroll
;                 for (int m = 0; m < 4; ++m)
; #pragma unroll
;                     for (int n = 0; n < 2; ++n) acc[a][b][m][n] = (f32x4){0.f, 0.f, 0.f, 0.f};
;         cur = nxt; cA = nA; cB = nB; ++ui;
.LBB0_471:
	s_ashr_i32 s23, s22, 31
	s_lshl_b64 s[24:25], s[22:23], 20
	s_add_u32 s24, s37, s24
	s_addc_u32 s25, s38, s25
	s_and_b64 s[26:27], s[4:5], exec
	s_cselect_b32 s3, s25, s15
	s_cselect_b32 s23, s24, s14
	s_ashr_i32 s21, s20, 31
	s_lshl_b64 s[26:27], s[20:21], 20
	s_add_u32 s26, s16, s26
	s_addc_u32 s27, s34, s27
	s_and_b64 s[30:31], s[4:5], exec
	s_cselect_b32 s21, s27, s29
	s_cselect_b32 s42, s26, s28
	s_add_u32 s14, s14, 0x80080
	s_addc_u32 s15, s15, 0
	s_add_u32 s43, s28, 0x100
	v_mov_b32_e32 v2, 0
	s_addc_u32 s56, s29, 0
	s_mov_b32 s57, -2
	v_mov_b32_e32 v3, v2
	v_mov_b64_e32 v[4:5], v[2:3]
	v_mov_b64_e32 v[6:7], v[2:3]
	v_mov_b64_e32 v[8:9], v[2:3]
	v_mov_b64_e32 v[10:11], v[2:3]
	v_mov_b64_e32 v[12:13], v[2:3]
	v_mov_b64_e32 v[14:15], v[2:3]
	v_mov_b64_e32 v[16:17], v[2:3]
	v_mov_b64_e32 v[18:19], v[2:3]
	v_mov_b64_e32 v[20:21], v[2:3]
	v_mov_b64_e32 v[22:23], v[2:3]
	v_mov_b64_e32 v[24:25], v[2:3]
	v_mov_b64_e32 v[26:27], v[2:3]
	v_mov_b64_e32 v[28:29], v[2:3]
	v_mov_b64_e32 v[30:31], v[2:3]
	v_mov_b64_e32 v[32:33], v[2:3]
	v_mov_b64_e32 v[34:35], v[2:3]
	v_mov_b64_e32 v[36:37], v[2:3]
	v_mov_b64_e32 v[38:39], v[2:3]
	v_mov_b64_e32 v[40:41], v[2:3]
	v_mov_b64_e32 v[42:43], v[2:3]
	v_mov_b64_e32 v[44:45], v[2:3]
	v_mov_b64_e32 v[46:47], v[2:3]
	v_mov_b64_e32 v[48:49], v[2:3]
	v_mov_b64_e32 v[50:51], v[2:3]
	v_mov_b64_e32 v[52:53], v[2:3]
	v_mov_b64_e32 v[54:55], v[2:3]
	v_mov_b64_e32 v[56:57], v[2:3]
	v_mov_b64_e32 v[58:59], v[2:3]
	v_mov_b64_e32 v[60:61], v[2:3]
	v_mov_b64_e32 v[62:63], v[2:3]
	v_mov_b64_e32 v[64:65], v[2:3]
	v_mov_b64_e32 v[66:67], v[2:3]
	v_mov_b64_e32 v[68:69], v[2:3]
	v_mov_b64_e32 v[70:71], v[2:3]
	v_mov_b64_e32 v[72:73], v[2:3]
	v_mov_b64_e32 v[74:75], v[2:3]
	v_mov_b64_e32 v[76:77], v[2:3]
	v_mov_b64_e32 v[78:79], v[2:3]
	v_mov_b64_e32 v[80:81], v[2:3]
	v_mov_b64_e32 v[82:83], v[2:3]
	v_mov_b64_e32 v[84:85], v[2:3]
	v_mov_b64_e32 v[86:87], v[2:3]
	v_mov_b64_e32 v[88:89], v[2:3]
	v_mov_b64_e32 v[90:91], v[2:3]
	v_mov_b64_e32 v[92:93], v[2:3]
	v_mov_b64_e32 v[94:95], v[2:3]
	v_mov_b64_e32 v[96:97], v[2:3]
	v_mov_b64_e32 v[98:99], v[2:3]
	v_mov_b64_e32 v[100:101], v[2:3]
	v_mov_b64_e32 v[102:103], v[2:3]
	v_mov_b64_e32 v[104:105], v[2:3]
	v_mov_b64_e32 v[106:107], v[2:3]
	v_mov_b64_e32 v[108:109], v[2:3]
	v_mov_b64_e32 v[110:111], v[2:3]
	v_mov_b64_e32 v[112:113], v[2:3]
	v_mov_b64_e32 v[114:115], v[2:3]
	v_mov_b64_e32 v[116:117], v[2:3]
	v_mov_b64_e32 v[118:119], v[2:3]
	v_mov_b64_e32 v[120:121], v[2:3]
	v_mov_b64_e32 v[122:123], v[2:3]
	v_mov_b64_e32 v[124:125], v[2:3]
	v_mov_b64_e32 v[126:127], v[2:3]
	v_mov_b64_e32 v[128:129], v[2:3]

; template <class Epi, class Sched, bool ALIGN_EPI = false, bool SP2 = false>
; __device__ __forceinline__ void gemm_phase(const int g_wave, PG8_LAS unsigned char* lds, const Gemm g, const Sched& S, const Epi& E) {
;     ...
; #pragma unroll
;         for (int a = 0; a < 2; ++a)
; #pragma unroll
;             for (int b = 0; b < 2; ++b)
; #pragma unroll
;                 for (int m = 0; m < 4; ++m)
; #pragma unroll
;                     for (int n = 0; n < 2; ++n) acc[a][b][m][n] = (f32x4){0.f, 0.f, 0.f, 0.f};
;         cur = nxt; cA = nA; cB = nB; ++ui;
.LBB0_568:
	s_ashr_i32 s15, s14, 31
	s_lshl_b64 s[22:23], s[14:15], 17
	s_add_u32 s22, s49, s22
	s_addc_u32 s23, s50, s23
	s_and_b64 s[24:25], s[8:9], exec
	s_cselect_b32 s15, s23, s27
	s_cselect_b32 s69, s22, s26
	s_ashr_i32 s3, s2, 31
	s_lshl_b64 s[24:25], s[2:3], 17
	s_add_u32 s24, s16, s24
	s_addc_u32 s25, s51, s25
	s_and_b64 s[28:29], s[8:9], exec
	v_mov_b32_e32 v2, 0
	s_cselect_b32 s3, s25, s21
	s_cselect_b32 s70, s24, s20
	s_mov_b32 s33, 0
	s_mov_b64 s[28:29], -1
	s_mov_b64 s[30:31], 0
	v_mov_b32_e32 v3, v2
	v_mov_b64_e32 v[4:5], v[2:3]
	v_mov_b64_e32 v[6:7], v[2:3]
	v_mov_b64_e32 v[8:9], v[2:3]
	v_mov_b64_e32 v[10:11], v[2:3]
	v_mov_b64_e32 v[12:13], v[2:3]
	v_mov_b64_e32 v[14:15], v[2:3]
	v_mov_b64_e32 v[16:17], v[2:3]
	v_mov_b64_e32 v[18:19], v[2:3]
	v_mov_b64_e32 v[20:21], v[2:3]
	v_mov_b64_e32 v[22:23], v[2:3]
	v_mov_b64_e32 v[24:25], v[2:3]
	v_mov_b64_e32 v[26:27], v[2:3]
	v_mov_b64_e32 v[28:29], v[2:3]
	v_mov_b64_e32 v[30:31], v[2:3]
	v_mov_b64_e32 v[32:33], v[2:3]
	v_mov_b64_e32 v[34:35], v[2:3]
	v_mov_b64_e32 v[36:37], v[2:3]
	v_mov_b64_e32 v[38:39], v[2:3]
	v_mov_b64_e32 v[40:41], v[2:3]
	v_mov_b64_e32 v[42:43], v[2:3]
	v_mov_b64_e32 v[44:45], v[2:3]
	v_mov_b64_e32 v[46:47], v[2:3]
	v_mov_b64_e32 v[48:49], v[2:3]
	v_mov_b64_e32 v[50:51], v[2:3]
	v_mov_b64_e32 v[52:53], v[2:3]
	v_mov_b64_e32 v[54:55], v[2:3]
	v_mov_b64_e32 v[56:57], v[2:3]
	v_mov_b64_e32 v[58:59], v[2:3]
	v_mov_b64_e32 v[60:61], v[2:3]
	v_mov_b64_e32 v[62:63], v[2:3]
	v_mov_b64_e32 v[64:65], v[2:3]
	v_mov_b64_e32 v[66:67], v[2:3]
	v_mov_b64_e32 v[68:69], v[2:3]
	v_mov_b64_e32 v[70:71], v[2:3]
	v_mov_b64_e32 v[72:73], v[2:3]
	v_mov_b64_e32 v[74:75], v[2:3]
	v_mov_b64_e32 v[76:77], v[2:3]
	v_mov_b64_e32 v[78:79], v[2:3]
	v_mov_b64_e32 v[80:81], v[2:3]
	v_mov_b64_e32 v[82:83], v[2:3]
	v_mov_b64_e32 v[84:85], v[2:3]
	v_mov_b64_e32 v[86:87], v[2:3]
	v_mov_b64_e32 v[88:89], v[2:3]
	v_mov_b64_e32 v[90:91], v[2:3]
	v_mov_b64_e32 v[92:93], v[2:3]
	v_mov_b64_e32 v[94:95], v[2:3]
	v_mov_b64_e32 v[96:97], v[2:3]
	v_mov_b64_e32 v[98:99], v[2:3]
	v_mov_b64_e32 v[100:101], v[2:3]
	v_mov_b64_e32 v[102:103], v[2:3]
	v_mov_b64_e32 v[104:105], v[2:3]
	v_mov_b64_e32 v[106:107], v[2:3]
	v_mov_b64_e32 v[108:109], v[2:3]
	v_mov_b64_e32 v[110:111], v[2:3]
	v_mov_b64_e32 v[112:113], v[2:3]
	v_mov_b64_e32 v[114:115], v[2:3]
	v_mov_b64_e32 v[116:117], v[2:3]
	v_mov_b64_e32 v[118:119], v[2:3]
	v_mov_b64_e32 v[120:121], v[2:3]
	v_mov_b64_e32 v[122:123], v[2:3]
	v_mov_b64_e32 v[124:125], v[2:3]
	v_mov_b64_e32 v[126:127], v[2:3]
	v_mov_b64_e32 v[128:129], v[2:3]

; template <class Epi, class Sched, bool ALIGN_EPI = false, bool SP2 = false>
; __device__ __forceinline__ void gemm_phase(const int g_wave, PG8_LAS unsigned char* lds, const Gemm g, const Sched& S, const Epi& E) {
;     ...
; #pragma unroll
;         for (int a = 0; a < 2; ++a)
; #pragma unroll
;             for (int b = 0; b < 2; ++b)
; #pragma unroll
;                 for (int m = 0; m < 4; ++m)
; #pragma unroll
;                     for (int n = 0; n < 2; ++n) acc[a][b][m][n] = (f32x4){0.f, 0.f, 0.f, 0.f};
;         cur = nxt; cA = nA; cB = nB; ++ui;
.LBB0_650:
	s_add_u32 s43, s4, 0x100
	v_mov_b32_e32 v2, 0
	s_addc_u32 s57, s5, 0
	s_mov_b32 s58, -2
	v_mov_b32_e32 v3, v2
	v_mov_b64_e32 v[4:5], v[2:3]
	v_mov_b64_e32 v[6:7], v[2:3]
	v_mov_b64_e32 v[8:9], v[2:3]
	v_mov_b64_e32 v[10:11], v[2:3]
	v_mov_b64_e32 v[12:13], v[2:3]
	v_mov_b64_e32 v[14:15], v[2:3]
	v_mov_b64_e32 v[16:17], v[2:3]
	v_mov_b64_e32 v[18:19], v[2:3]
	v_mov_b64_e32 v[20:21], v[2:3]
	v_mov_b64_e32 v[22:23], v[2:3]
	v_mov_b64_e32 v[24:25], v[2:3]
	v_mov_b64_e32 v[26:27], v[2:3]
	v_mov_b64_e32 v[28:29], v[2:3]
	v_mov_b64_e32 v[30:31], v[2:3]
	v_mov_b64_e32 v[32:33], v[2:3]
	v_mov_b64_e32 v[34:35], v[2:3]
	v_mov_b64_e32 v[36:37], v[2:3]
	v_mov_b64_e32 v[38:39], v[2:3]
	v_mov_b64_e32 v[40:41], v[2:3]
	v_mov_b64_e32 v[42:43], v[2:3]
	v_mov_b64_e32 v[44:45], v[2:3]
	v_mov_b64_e32 v[46:47], v[2:3]
	v_mov_b64_e32 v[48:49], v[2:3]
	v_mov_b64_e32 v[50:51], v[2:3]
	v_mov_b64_e32 v[52:53], v[2:3]
	v_mov_b64_e32 v[54:55], v[2:3]
	v_mov_b64_e32 v[56:57], v[2:3]
	v_mov_b64_e32 v[58:59], v[2:3]
	v_mov_b64_e32 v[60:61], v[2:3]
	v_mov_b64_e32 v[62:63], v[2:3]
	v_mov_b64_e32 v[64:65], v[2:3]
	v_mov_b64_e32 v[66:67], v[2:3]
	v_mov_b64_e32 v[68:69], v[2:3]
	v_mov_b64_e32 v[70:71], v[2:3]
	v_mov_b64_e32 v[72:73], v[2:3]
	v_mov_b64_e32 v[74:75], v[2:3]
	v_mov_b64_e32 v[76:77], v[2:3]
	v_mov_b64_e32 v[78:79], v[2:3]
	v_mov_b64_e32 v[80:81], v[2:3]
	v_mov_b64_e32 v[82:83], v[2:3]
	v_mov_b64_e32 v[84:85], v[2:3]
	v_mov_b64_e32 v[86:87], v[2:3]
	v_mov_b64_e32 v[88:89], v[2:3]
	v_mov_b64_e32 v[90:91], v[2:3]
	v_mov_b64_e32 v[92:93], v[2:3]
	v_mov_b64_e32 v[94:95], v[2:3]
	v_mov_b64_e32 v[96:97], v[2:3]
	v_mov_b64_e32 v[98:99], v[2:3]
	v_mov_b64_e32 v[100:101], v[2:3]
	v_mov_b64_e32 v[102:103], v[2:3]
	v_mov_b64_e32 v[104:105], v[2:3]
	v_mov_b64_e32 v[106:107], v[2:3]
	v_mov_b64_e32 v[108:109], v[2:3]
	v_mov_b64_e32 v[110:111], v[2:3]
	v_mov_b64_e32 v[112:113], v[2:3]
	v_mov_b64_e32 v[114:115], v[2:3]
	v_mov_b64_e32 v[116:117], v[2:3]
	v_mov_b64_e32 v[118:119], v[2:3]
	v_mov_b64_e32 v[120:121], v[2:3]
	v_mov_b64_e32 v[122:123], v[2:3]
	v_mov_b64_e32 v[124:125], v[2:3]
	v_mov_b64_e32 v[126:127], v[2:3]
	v_mov_b64_e32 v[128:129], v[2:3]

; template <class Epi, class Sched, bool ALIGN_EPI = false, bool SP2 = false>
; __device__ __forceinline__ void gemm_phase(const int g_wave, PG8_LAS unsigned char* lds, const Gemm g, const Sched& S, const Epi& E) {
;     ...
;         const bool has_next = S.next(ui + 1, nxt);
;         const char* nA = has_next ? (const char*)g.A + (size_t)nxt.pm * tstep : cA; const char* nB = has_next ? (const char*)g.Bt + (size_t)nxt.pn * tstep : cB;
;         for (int t = 0; t < nt; t += 2) {
;             const bool last = (t == nt - 2);
;             const char* a1 = cA + (size_t)(t + 1) * kstep;
;             const char* a2 = last ? nA : cA + (size_t)(t + 2) * kstep; const char* b2 = last ? nB : cB + (size_t)(t + 2) * kstep;
;             const char* a3 = a2 + kstep; const char* b3 = b2 + kstep;
;     ...
; #pragma unroll
;         for (int a = 0; a < 2; ++a)
; #pragma unroll
;             for (int b = 0; b < 2; ++b)
; #pragma unroll
;                 for (int m = 0; m < 4; ++m)
; #pragma unroll
;                     for (int n = 0; n < 2; ++n) acc[a][b][m][n] = (f32x4){0.f, 0.f, 0.f, 0.f};
.LBB0_734:
	s_ashr_i32 s25, s24, 31
	s_lshl_b64 s[26:27], s[24:25], 20
	s_add_u32 s26, s36, s26
	s_addc_u32 s27, s37, s27
	s_and_b64 s[28:29], s[8:9], exec
	s_cselect_b32 s25, s27, s5
	s_cselect_b32 s42, s26, s4
	s_ashr_i32 s23, s22, 31
	s_lshl_b64 s[28:29], s[22:23], 20
	s_add_u32 s28, s38, s28
	s_addc_u32 s29, s39, s29
	s_and_b64 s[30:31], s[8:9], exec
	s_cselect_b32 s23, s29, s15
	s_cselect_b32 s43, s28, s14
	s_add_u32 s4, s4, 0x80080
	s_addc_u32 s5, s5, 0
	s_add_u32 s51, s14, 0x100
	v_mov_b32_e32 v2, 0
	s_addc_u32 s56, s15, 0
	s_mov_b32 s57, -2
	v_mov_b32_e32 v3, v2
	v_mov_b64_e32 v[4:5], v[2:3]
	v_mov_b64_e32 v[6:7], v[2:3]
	v_mov_b64_e32 v[8:9], v[2:3]
	v_mov_b64_e32 v[10:11], v[2:3]
	v_mov_b64_e32 v[12:13], v[2:3]
	v_mov_b64_e32 v[14:15], v[2:3]
	v_mov_b64_e32 v[16:17], v[2:3]
	v_mov_b64_e32 v[18:19], v[2:3]
	v_mov_b64_e32 v[20:21], v[2:3]
	v_mov_b64_e32 v[22:23], v[2:3]
	v_mov_b64_e32 v[24:25], v[2:3]
	v_mov_b64_e32 v[26:27], v[2:3]
	v_mov_b64_e32 v[28:29], v[2:3]
	v_mov_b64_e32 v[30:31], v[2:3]
	v_mov_b64_e32 v[32:33], v[2:3]
	v_mov_b64_e32 v[34:35], v[2:3]
	v_mov_b64_e32 v[36:37], v[2:3]
	v_mov_b64_e32 v[38:39], v[2:3]
	v_mov_b64_e32 v[40:41], v[2:3]
	v_mov_b64_e32 v[42:43], v[2:3]
	v_mov_b64_e32 v[44:45], v[2:3]
	v_mov_b64_e32 v[46:47], v[2:3]
	v_mov_b64_e32 v[48:49], v[2:3]
	v_mov_b64_e32 v[50:51], v[2:3]
	v_mov_b64_e32 v[52:53], v[2:3]
	v_mov_b64_e32 v[54:55], v[2:3]
	v_mov_b64_e32 v[56:57], v[2:3]
	v_mov_b64_e32 v[58:59], v[2:3]
	v_mov_b64_e32 v[60:61], v[2:3]
	v_mov_b64_e32 v[62:63], v[2:3]
	v_mov_b64_e32 v[64:65], v[2:3]
	v_mov_b64_e32 v[66:67], v[2:3]
	v_mov_b64_e32 v[68:69], v[2:3]
	v_mov_b64_e32 v[70:71], v[2:3]
	v_mov_b64_e32 v[72:73], v[2:3]
	v_mov_b64_e32 v[74:75], v[2:3]
	v_mov_b64_e32 v[76:77], v[2:3]
	v_mov_b64_e32 v[78:79], v[2:3]
	v_mov_b64_e32 v[80:81], v[2:3]
	v_mov_b64_e32 v[82:83], v[2:3]
	v_mov_b64_e32 v[84:85], v[2:3]
	v_mov_b64_e32 v[86:87], v[2:3]
	v_mov_b64_e32 v[88:89], v[2:3]
	v_mov_b64_e32 v[90:91], v[2:3]
	v_mov_b64_e32 v[92:93], v[2:3]
	v_mov_b64_e32 v[94:95], v[2:3]
	v_mov_b64_e32 v[96:97], v[2:3]
	v_mov_b64_e32 v[98:99], v[2:3]
	v_mov_b64_e32 v[100:101], v[2:3]
	v_mov_b64_e32 v[102:103], v[2:3]
	v_mov_b64_e32 v[104:105], v[2:3]
	v_mov_b64_e32 v[106:107], v[2:3]
	v_mov_b64_e32 v[108:109], v[2:3]
	v_mov_b64_e32 v[110:111], v[2:3]
	v_mov_b64_e32 v[112:113], v[2:3]
	v_mov_b64_e32 v[114:115], v[2:3]
	v_mov_b64_e32 v[116:117], v[2:3]
	v_mov_b64_e32 v[118:119], v[2:3]
	v_mov_b64_e32 v[120:121], v[2:3]
	v_mov_b64_e32 v[122:123], v[2:3]
	v_mov_b64_e32 v[124:125], v[2:3]
	v_mov_b64_e32 v[126:127], v[2:3]
	v_mov_b64_e32 v[128:129], v[2:3]

; template <class Epi, class Sched, bool ALIGN_EPI = false, bool SP2 = false>
; __device__ __forceinline__ void gemm_phase(const int g_wave, PG8_LAS unsigned char* lds, const Gemm g, const Sched& S, const Epi& E) {
;     ...
;         const bool has_next = S.next(ui + 1, nxt);
;         const char* nA = has_next ? (const char*)g.A + (size_t)nxt.pm * tstep : cA; const char* nB = has_next ? (const char*)g.Bt + (size_t)nxt.pn * tstep : cB;
;         for (int t = 0; t < nt; t += 2) {
;             const bool last = (t == nt - 2);
;             const char* a1 = cA + (size_t)(t + 1) * kstep;
;             const char* a2 = last ? nA : cA + (size_t)(t + 2) * kstep; const char* b2 = last ? nB : cB + (size_t)(t + 2) * kstep;
;             const char* a3 = a2 + kstep; const char* b3 = b2 + kstep;
;     ...
; #pragma unroll
;         for (int a = 0; a < 2; ++a)
; #pragma unroll
;             for (int b = 0; b < 2; ++b)
; #pragma unroll
;                 for (int m = 0; m < 4; ++m)
; #pragma unroll
;                     for (int n = 0; n < 2; ++n) acc[a][b][m][n] = (f32x4){0.f, 0.f, 0.f, 0.f};
.LBB0_1274:
	s_ashr_i32 s25, s24, 31
	s_lshl_b64 s[26:27], s[24:25], 20
	s_add_u32 s26, s38, s26
	s_addc_u32 s27, s39, s27
	s_and_b64 s[28:29], s[8:9], exec
	s_cselect_b32 s1, s27, s3
	s_cselect_b32 s25, s26, s2
	s_ashr_i32 s23, s22, 31
	s_lshl_b64 s[28:29], s[22:23], 20
	s_add_u32 s28, s41, s28
	s_addc_u32 s29, s44, s29
	s_and_b64 s[34:35], s[8:9], exec
	s_cselect_b32 s23, s29, s31
	s_cselect_b32 s42, s28, s30
	s_add_u32 s2, s2, 0x80080
	s_addc_u32 s3, s3, 0
	s_add_u32 s43, s30, 0x100
	v_mov_b32_e32 v2, 0
	s_addc_u32 s57, s31, 0
	s_mov_b32 s58, -2
	v_mov_b32_e32 v3, v2
	v_mov_b64_e32 v[4:5], v[2:3]
	v_mov_b64_e32 v[6:7], v[2:3]
	v_mov_b64_e32 v[8:9], v[2:3]
	v_mov_b64_e32 v[10:11], v[2:3]
	v_mov_b64_e32 v[12:13], v[2:3]
	v_mov_b64_e32 v[14:15], v[2:3]
	v_mov_b64_e32 v[16:17], v[2:3]
	v_mov_b64_e32 v[18:19], v[2:3]
	v_mov_b64_e32 v[20:21], v[2:3]
	v_mov_b64_e32 v[22:23], v[2:3]
	v_mov_b64_e32 v[24:25], v[2:3]
	v_mov_b64_e32 v[26:27], v[2:3]
	v_mov_b64_e32 v[28:29], v[2:3]
	v_mov_b64_e32 v[30:31], v[2:3]
	v_mov_b64_e32 v[32:33], v[2:3]
	v_mov_b64_e32 v[34:35], v[2:3]
	v_mov_b64_e32 v[36:37], v[2:3]
	v_mov_b64_e32 v[38:39], v[2:3]
	v_mov_b64_e32 v[40:41], v[2:3]
	v_mov_b64_e32 v[42:43], v[2:3]
	v_mov_b64_e32 v[44:45], v[2:3]
	v_mov_b64_e32 v[46:47], v[2:3]
	v_mov_b64_e32 v[48:49], v[2:3]
	v_mov_b64_e32 v[50:51], v[2:3]
	v_mov_b64_e32 v[52:53], v[2:3]
	v_mov_b64_e32 v[54:55], v[2:3]
	v_mov_b64_e32 v[56:57], v[2:3]
	v_mov_b64_e32 v[58:59], v[2:3]
	v_mov_b64_e32 v[60:61], v[2:3]
	v_mov_b64_e32 v[62:63], v[2:3]
	v_mov_b64_e32 v[64:65], v[2:3]
	v_mov_b64_e32 v[66:67], v[2:3]
	v_mov_b64_e32 v[68:69], v[2:3]
	v_mov_b64_e32 v[70:71], v[2:3]
	v_mov_b64_e32 v[72:73], v[2:3]
	v_mov_b64_e32 v[74:75], v[2:3]
	v_mov_b64_e32 v[76:77], v[2:3]
	v_mov_b64_e32 v[78:79], v[2:3]
	v_mov_b64_e32 v[80:81], v[2:3]
	v_mov_b64_e32 v[82:83], v[2:3]
	v_mov_b64_e32 v[84:85], v[2:3]
	v_mov_b64_e32 v[86:87], v[2:3]
	v_mov_b64_e32 v[88:89], v[2:3]
	v_mov_b64_e32 v[90:91], v[2:3]
	v_mov_b64_e32 v[92:93], v[2:3]
	v_mov_b64_e32 v[94:95], v[2:3]
	v_mov_b64_e32 v[96:97], v[2:3]
	v_mov_b64_e32 v[98:99], v[2:3]
	v_mov_b64_e32 v[100:101], v[2:3]
	v_mov_b64_e32 v[102:103], v[2:3]
	v_mov_b64_e32 v[104:105], v[2:3]
	v_mov_b64_e32 v[106:107], v[2:3]
	v_mov_b64_e32 v[108:109], v[2:3]
	v_mov_b64_e32 v[110:111], v[2:3]
	v_mov_b64_e32 v[112:113], v[2:3]
	v_mov_b64_e32 v[114:115], v[2:3]
	v_mov_b64_e32 v[116:117], v[2:3]
	v_mov_b64_e32 v[118:119], v[2:3]
	v_mov_b64_e32 v[120:121], v[2:3]
	v_mov_b64_e32 v[122:123], v[2:3]
	v_mov_b64_e32 v[124:125], v[2:3]
	v_mov_b64_e32 v[126:127], v[2:3]
	v_mov_b64_e32 v[128:129], v[2:3]

; template <class Epi, class Sched, bool ALIGN_EPI = false, bool SP2 = false>
; __device__ __forceinline__ void gemm_phase(const int g_wave, PG8_LAS unsigned char* lds, const Gemm g, const Sched& S, const Epi& E) {
;     ...
;         const bool has_next = S.next(ui + 1, nxt);
;         const char* nA = has_next ? (const char*)g.A + (size_t)nxt.pm * tstep : cA; const char* nB = has_next ? (const char*)g.Bt + (size_t)nxt.pn * tstep : cB;
;         for (int t = 0; t < nt; t += 2) {
;             const bool last = (t == nt - 2);
;             const char* a1 = cA + (size_t)(t + 1) * kstep;
;             const char* a2 = last ? nA : cA + (size_t)(t + 2) * kstep; const char* b2 = last ? nB : cB + (size_t)(t + 2) * kstep;
;             const char* a3 = a2 + kstep; const char* b3 = b2 + kstep;
;     ...
; #pragma unroll
;         for (int a = 0; a < 2; ++a)
; #pragma unroll
;             for (int b = 0; b < 2; ++b)
; #pragma unroll
;                 for (int m = 0; m < 4; ++m)
; #pragma unroll
;                     for (int n = 0; n < 2; ++n) acc[a][b][m][n] = (f32x4){0.f, 0.f, 0.f, 0.f};
.LBB0_1358:
	s_ashr_i32 s23, s22, 31
	s_lshl_b64 s[24:25], s[22:23], 20
	s_add_u32 s24, s34, s24
	s_addc_u32 s25, s35, s25
	s_and_b64 s[26:27], s[6:7], exec
	s_cselect_b32 s3, s25, s5
	s_cselect_b32 s23, s24, s4
	s_ashr_i32 s21, s20, 31
	s_lshl_b64 s[26:27], s[20:21], 20
	s_add_u32 s26, s36, s26
	s_addc_u32 s27, s37, s27
	s_and_b64 s[28:29], s[6:7], exec
	s_cselect_b32 s21, s27, s15
	s_cselect_b32 s42, s26, s14
	s_add_u32 s4, s4, 0x80080
	s_addc_u32 s5, s5, 0
	s_add_u32 s43, s14, 0x100
	v_mov_b32_e32 v2, 0
	s_addc_u32 s50, s15, 0
	s_mov_b32 s51, -2
	v_mov_b32_e32 v3, v2
	v_mov_b64_e32 v[4:5], v[2:3]
	v_mov_b64_e32 v[6:7], v[2:3]
	v_mov_b64_e32 v[8:9], v[2:3]
	v_mov_b64_e32 v[10:11], v[2:3]
	v_mov_b64_e32 v[12:13], v[2:3]
	v_mov_b64_e32 v[14:15], v[2:3]
	v_mov_b64_e32 v[16:17], v[2:3]
	v_mov_b64_e32 v[18:19], v[2:3]
	v_mov_b64_e32 v[20:21], v[2:3]
	v_mov_b64_e32 v[22:23], v[2:3]
	v_mov_b64_e32 v[24:25], v[2:3]
	v_mov_b64_e32 v[26:27], v[2:3]
	v_mov_b64_e32 v[28:29], v[2:3]
	v_mov_b64_e32 v[30:31], v[2:3]
	v_mov_b64_e32 v[32:33], v[2:3]
	v_mov_b64_e32 v[34:35], v[2:3]
	v_mov_b64_e32 v[36:37], v[2:3]
	v_mov_b64_e32 v[38:39], v[2:3]
	v_mov_b64_e32 v[40:41], v[2:3]
	v_mov_b64_e32 v[42:43], v[2:3]
	v_mov_b64_e32 v[44:45], v[2:3]
	v_mov_b64_e32 v[46:47], v[2:3]
	v_mov_b64_e32 v[48:49], v[2:3]
	v_mov_b64_e32 v[50:51], v[2:3]
	v_mov_b64_e32 v[52:53], v[2:3]
	v_mov_b64_e32 v[54:55], v[2:3]
	v_mov_b64_e32 v[56:57], v[2:3]
	v_mov_b64_e32 v[58:59], v[2:3]
	v_mov_b64_e32 v[60:61], v[2:3]
	v_mov_b64_e32 v[62:63], v[2:3]
	v_mov_b64_e32 v[64:65], v[2:3]
	v_mov_b64_e32 v[66:67], v[2:3]
	v_mov_b64_e32 v[68:69], v[2:3]
	v_mov_b64_e32 v[70:71], v[2:3]
	v_mov_b64_e32 v[72:73], v[2:3]
	v_mov_b64_e32 v[74:75], v[2:3]
	v_mov_b64_e32 v[76:77], v[2:3]
	v_mov_b64_e32 v[78:79], v[2:3]
	v_mov_b64_e32 v[80:81], v[2:3]
	v_mov_b64_e32 v[82:83], v[2:3]
	v_mov_b64_e32 v[84:85], v[2:3]
	v_mov_b64_e32 v[86:87], v[2:3]
	v_mov_b64_e32 v[88:89], v[2:3]
	v_mov_b64_e32 v[90:91], v[2:3]
	v_mov_b64_e32 v[92:93], v[2:3]
	v_mov_b64_e32 v[94:95], v[2:3]
	v_mov_b64_e32 v[96:97], v[2:3]
	v_mov_b64_e32 v[98:99], v[2:3]
	v_mov_b64_e32 v[100:101], v[2:3]
	v_mov_b64_e32 v[102:103], v[2:3]
	v_mov_b64_e32 v[104:105], v[2:3]
	v_mov_b64_e32 v[106:107], v[2:3]
	v_mov_b64_e32 v[108:109], v[2:3]
	v_mov_b64_e32 v[110:111], v[2:3]
	v_mov_b64_e32 v[112:113], v[2:3]
	v_mov_b64_e32 v[114:115], v[2:3]
	v_mov_b64_e32 v[116:117], v[2:3]
	v_mov_b64_e32 v[118:119], v[2:3]
	v_mov_b64_e32 v[120:121], v[2:3]
	v_mov_b64_e32 v[122:123], v[2:3]
	v_mov_b64_e32 v[124:125], v[2:3]
	v_mov_b64_e32 v[126:127], v[2:3]
	v_mov_b64_e32 v[128:129], v[2:3]

; template <class Epi, class Sched, bool ALIGN_EPI = false, bool SP2 = false>
; __device__ __forceinline__ void gemm_phase(const int g_wave, PG8_LAS unsigned char* lds, const Gemm g, const Sched& S, const Epi& E) {
;     ...
;             const char* a3 = a2 + kstep; const char* b3 = b2 + kstep;
;     ...
; #pragma unroll
;         for (int a = 0; a < 2; ++a)
; #pragma unroll
;             for (int b = 0; b < 2; ++b)
; #pragma unroll
;                 for (int m = 0; m < 4; ++m)
; #pragma unroll
;                     for (int n = 0; n < 2; ++n) acc[a][b][m][n] = (f32x4){0.f, 0.f, 0.f, 0.f};
.LBB0_1513:
	s_add_u32 s43, s14, 0x100
	v_mov_b32_e32 v2, 0
	s_addc_u32 s57, s15, 0
	s_mov_b32 s58, -2
	v_mov_b32_e32 v3, v2
	v_mov_b64_e32 v[4:5], v[2:3]
	v_mov_b64_e32 v[6:7], v[2:3]
	v_mov_b64_e32 v[8:9], v[2:3]
	v_mov_b64_e32 v[10:11], v[2:3]
	v_mov_b64_e32 v[12:13], v[2:3]
	v_mov_b64_e32 v[14:15], v[2:3]
	v_mov_b64_e32 v[16:17], v[2:3]
	v_mov_b64_e32 v[18:19], v[2:3]
	v_mov_b64_e32 v[20:21], v[2:3]
	v_mov_b64_e32 v[22:23], v[2:3]
	v_mov_b64_e32 v[24:25], v[2:3]
	v_mov_b64_e32 v[26:27], v[2:3]
	v_mov_b64_e32 v[28:29], v[2:3]
	v_mov_b64_e32 v[30:31], v[2:3]
	v_mov_b64_e32 v[32:33], v[2:3]
	v_mov_b64_e32 v[34:35], v[2:3]
	v_mov_b64_e32 v[36:37], v[2:3]
	v_mov_b64_e32 v[38:39], v[2:3]
	v_mov_b64_e32 v[40:41], v[2:3]
	v_mov_b64_e32 v[42:43], v[2:3]
	v_mov_b64_e32 v[44:45], v[2:3]
	v_mov_b64_e32 v[46:47], v[2:3]
	v_mov_b64_e32 v[48:49], v[2:3]
	v_mov_b64_e32 v[50:51], v[2:3]
	v_mov_b64_e32 v[52:53], v[2:3]
	v_mov_b64_e32 v[54:55], v[2:3]
	v_mov_b64_e32 v[56:57], v[2:3]
	v_mov_b64_e32 v[58:59], v[2:3]
	v_mov_b64_e32 v[60:61], v[2:3]
	v_mov_b64_e32 v[62:63], v[2:3]
	v_mov_b64_e32 v[64:65], v[2:3]
	v_mov_b64_e32 v[66:67], v[2:3]
	v_mov_b64_e32 v[68:69], v[2:3]
	v_mov_b64_e32 v[70:71], v[2:3]
	v_mov_b64_e32 v[72:73], v[2:3]
	v_mov_b64_e32 v[74:75], v[2:3]
	v_mov_b64_e32 v[76:77], v[2:3]
	v_mov_b64_e32 v[78:79], v[2:3]
	v_mov_b64_e32 v[80:81], v[2:3]
	v_mov_b64_e32 v[82:83], v[2:3]
	v_mov_b64_e32 v[84:85], v[2:3]
	v_mov_b64_e32 v[86:87], v[2:3]
	v_mov_b64_e32 v[88:89], v[2:3]
	v_mov_b64_e32 v[90:91], v[2:3]
	v_mov_b64_e32 v[92:93], v[2:3]
	v_mov_b64_e32 v[94:95], v[2:3]
	v_mov_b64_e32 v[96:97], v[2:3]
	v_mov_b64_e32 v[98:99], v[2:3]
	v_mov_b64_e32 v[100:101], v[2:3]
	v_mov_b64_e32 v[102:103], v[2:3]
	v_mov_b64_e32 v[104:105], v[2:3]
	v_mov_b64_e32 v[106:107], v[2:3]
	v_mov_b64_e32 v[108:109], v[2:3]
	v_mov_b64_e32 v[110:111], v[2:3]
	v_mov_b64_e32 v[112:113], v[2:3]
	v_mov_b64_e32 v[114:115], v[2:3]
	v_mov_b64_e32 v[116:117], v[2:3]
	v_mov_b64_e32 v[118:119], v[2:3]
	v_mov_b64_e32 v[120:121], v[2:3]
	v_mov_b64_e32 v[122:123], v[2:3]
	v_mov_b64_e32 v[124:125], v[2:3]
	v_mov_b64_e32 v[126:127], v[2:3]
	v_mov_b64_e32 v[128:129], v[2:3]

; template <class Epi, class Sched, bool ALIGN_EPI = false, bool SP2 = false>
; __device__ __forceinline__ void gemm_phase(const int g_wave, PG8_LAS unsigned char* lds, const Gemm g, const Sched& S, const Epi& E) {
;     ...
;         const bool has_next = S.next(ui + 1, nxt);
;         const char* nA = has_next ? (const char*)g.A + (size_t)nxt.pm * tstep : cA; const char* nB = has_next ? (const char*)g.Bt + (size_t)nxt.pn * tstep : cB;
;         for (int t = 0; t < nt; t += 2) {
;             const bool last = (t == nt - 2);
;             const char* a1 = cA + (size_t)(t + 1) * kstep;
;             const char* a2 = last ? nA : cA + (size_t)(t + 2) * kstep; const char* b2 = last ? nB : cB + (size_t)(t + 2) * kstep;
;             const char* a3 = a2 + kstep; const char* b3 = b2 + kstep;
;     ...
; #pragma unroll
;         for (int a = 0; a < 2; ++a)
; #pragma unroll
;             for (int b = 0; b < 2; ++b)
; #pragma unroll
;                 for (int m = 0; m < 4; ++m)
; #pragma unroll
;                     for (int n = 0; n < 2; ++n) acc[a][b][m][n] = (f32x4){0.f, 0.f, 0.f, 0.f};
.LBB0_1607:
	s_ashr_i32 s29, s28, 31
	s_lshl_b64 s[30:31], s[28:29], 20
	s_add_u32 s30, s41, s30
	s_addc_u32 s31, s44, s31
	s_and_b64 s[36:37], s[6:7], exec
	s_cselect_b32 s1, s31, s3
	s_cselect_b32 s9, s30, s2
	s_ashr_i32 s27, s26, 31
	s_lshl_b64 s[36:37], s[26:27], 20
	s_add_u32 s76, s45, s36
	s_addc_u32 s77, s46, s37
	s_and_b64 s[36:37], s[6:7], exec
	s_cselect_b32 s27, s77, s35
	s_cselect_b32 s29, s76, s34
	s_add_u32 s2, s2, 0x80080
	s_addc_u32 s3, s3, 0
	s_add_u32 s42, s34, 0x100
	v_mov_b32_e32 v2, 0
	s_addc_u32 s43, s35, 0
	s_mov_b32 s59, -2
	v_mov_b32_e32 v3, v2
	v_mov_b64_e32 v[4:5], v[2:3]
	v_mov_b64_e32 v[6:7], v[2:3]
	v_mov_b64_e32 v[8:9], v[2:3]
	v_mov_b64_e32 v[10:11], v[2:3]
	v_mov_b64_e32 v[12:13], v[2:3]
	v_mov_b64_e32 v[14:15], v[2:3]
	v_mov_b64_e32 v[16:17], v[2:3]
	v_mov_b64_e32 v[18:19], v[2:3]
	v_mov_b64_e32 v[20:21], v[2:3]
	v_mov_b64_e32 v[22:23], v[2:3]
	v_mov_b64_e32 v[24:25], v[2:3]
	v_mov_b64_e32 v[26:27], v[2:3]
	v_mov_b64_e32 v[28:29], v[2:3]
	v_mov_b64_e32 v[30:31], v[2:3]
	v_mov_b64_e32 v[32:33], v[2:3]
	v_mov_b64_e32 v[34:35], v[2:3]
	v_mov_b64_e32 v[36:37], v[2:3]
	v_mov_b64_e32 v[38:39], v[2:3]
	v_mov_b64_e32 v[40:41], v[2:3]
	v_mov_b64_e32 v[42:43], v[2:3]
	v_mov_b64_e32 v[44:45], v[2:3]
	v_mov_b64_e32 v[46:47], v[2:3]
	v_mov_b64_e32 v[48:49], v[2:3]
	v_mov_b64_e32 v[50:51], v[2:3]
	v_mov_b64_e32 v[52:53], v[2:3]
	v_mov_b64_e32 v[54:55], v[2:3]
	v_mov_b64_e32 v[56:57], v[2:3]
	v_mov_b64_e32 v[58:59], v[2:3]
	v_mov_b64_e32 v[60:61], v[2:3]
	v_mov_b64_e32 v[62:63], v[2:3]
	v_mov_b64_e32 v[64:65], v[2:3]
	v_mov_b64_e32 v[66:67], v[2:3]
	v_mov_b64_e32 v[68:69], v[2:3]
	v_mov_b64_e32 v[70:71], v[2:3]
	v_mov_b64_e32 v[72:73], v[2:3]
	v_mov_b64_e32 v[74:75], v[2:3]
	v_mov_b64_e32 v[76:77], v[2:3]
	v_mov_b64_e32 v[78:79], v[2:3]
	v_mov_b64_e32 v[80:81], v[2:3]
	v_mov_b64_e32 v[82:83], v[2:3]
	v_mov_b64_e32 v[84:85], v[2:3]
	v_mov_b64_e32 v[86:87], v[2:3]
	v_mov_b64_e32 v[88:89], v[2:3]
	v_mov_b64_e32 v[90:91], v[2:3]
	v_mov_b64_e32 v[92:93], v[2:3]
	v_mov_b64_e32 v[94:95], v[2:3]
	v_mov_b64_e32 v[96:97], v[2:3]
	v_mov_b64_e32 v[98:99], v[2:3]
	v_mov_b64_e32 v[100:101], v[2:3]
	v_mov_b64_e32 v[102:103], v[2:3]
	v_mov_b64_e32 v[104:105], v[2:3]
	v_mov_b64_e32 v[106:107], v[2:3]
	v_mov_b64_e32 v[108:109], v[2:3]
	v_mov_b64_e32 v[110:111], v[2:3]
	v_mov_b64_e32 v[112:113], v[2:3]
	v_mov_b64_e32 v[114:115], v[2:3]
	v_mov_b64_e32 v[116:117], v[2:3]
	v_mov_b64_e32 v[118:119], v[2:3]
	v_mov_b64_e32 v[120:121], v[2:3]
	v_mov_b64_e32 v[122:123], v[2:3]
	v_mov_b64_e32 v[124:125], v[2:3]
	v_mov_b64_e32 v[126:127], v[2:3]
	v_mov_b64_e32 v[128:129], v[2:3]
